# v33 + write-through sc1 on d_out-only stores (final norm y, KV f32 outputs): never re-read by the kernel
# speedup vs baseline: 1.0027x; 1.0027x over previous
; __device__ __forceinline__ unsigned cvt_pk_bf16(float lo, float hi) { unsigned r; asm volatile("v_cvt_pk_bf16_f32 %0, %1, %2" : "=v"(r) : "v"(lo), "v"(hi)); return r; }
;     __device__ __forceinline__ void operator()(Acc& acc, const Unit& u, int wr, int wc, int fr, int fq, LAS unsigned char*, const LAS float* rst) const {
;         const int l = u.pn >> 3, isV = (u.pn >> 2) & 1, h = u.pn & 3;
;         const int row0 = u.pm * 256 + wr * 64 + fr, cc0 = h * 256 + wc * 32 + 4 * fq;
;         float* dst = (isV ? dV : dK) + (size_t)l * 2048 * 1024;
; #pragma unroll
;         for (int ai = 0; ai < 2; ++ai)
; #pragma unroll
;             for (int m = 0; m < 4; ++m) {
;                 const int row = row0 + ai * 128 + m * 16; const float rs = rsm[row];
; #pragma unroll
;                 for (int bj = 0; bj < 2; ++bj)
; #pragma unroll
;                     for (int n = 0; n < 2; ++n) { const f32x4 v = acc[ai][bj][m][n] * rs; const int cc = cc0 + bj * 128 + n * 16;
;                         *(f32x4*)(dst + (size_t)row * 1024 + cc) = v;
;                         if (!isV) { u32x2 w; w.x = cvt_pk_bf16(v[0], v[1]); w.y = cvt_pk_bf16(v[2], v[3]); *(u32x2*)(Kb + ((size_t)l * 2048 + row) * 1024 + cc) = w; }
.LBB0_202:
	v_lshl_add_u32 v138, s10, 8, v149
	v_ashrrev_i32_e32 v139, 31, v138
	v_lshl_add_u64 v[140:141], v[138:139], 2, s[6:7]
	global_load_dword v142, v[140:141], off
	global_load_dword v240, v[140:141], off offset:64
	global_load_dword v241, v[140:141], off offset:128
	global_load_dword v242, v[140:141], off offset:192
	global_load_dword v243, v[140:141], off offset:512
	global_load_dword v244, v[140:141], off offset:576
	global_load_dword v245, v[140:141], off offset:640
	global_load_dword v246, v[140:141], off offset:704
	s_lshl_b32 s1, s0, 8
	s_ashr_i32 s22, s0, 3
	s_and_b32 s20, s0, 4
	s_and_b32 s1, s1, 0x300
	s_bitcmp1_b32 s0, 2
	s_cselect_b64 s[10:11], -1, 0
	s_cmp_eq_u32 s20, 0
	s_cselect_b32 s0, s44, 0x9100000
	s_add_u32 s20, s48, s0
	s_addc_u32 s21, s49, 0
	s_ashr_i32 s23, s22, 31
	v_or_b32_e32 v155, s1, v151
	s_lshl_b64 s[0:1], s[22:23], 23
	s_add_u32 s20, s20, s0
	v_lshlrev_b64 v[144:145], 12, v[138:139]
	s_addc_u32 s21, s21, s1
	v_lshlrev_b32_e32 v132, 2, v155
	v_lshl_add_u64 v[144:145], s[20:21], 0, v[144:145]
	s_mov_b64 s[24:25], -1
	s_and_b64 vcc, exec, s[10:11]
	v_lshl_add_u64 v[144:145], v[144:145], 0, v[132:133]
	s_waitcnt vmcnt(0)
	v_pk_mul_f32 v[126:127], v[126:127], v[142:143] op_sel_hi:[1,0]
	v_pk_mul_f32 v[124:125], v[124:125], v[142:143] op_sel_hi:[1,0]
	global_store_dwordx4 v[144:145], v[124:127], off sc1
	s_cbranch_vccz .LBB0_204
	v_cvt_pk_bf16_f32 v146, v124, v125
	v_cvt_pk_bf16_f32 v147, v126, v127
	s_mov_b64 s[24:25], 0

; __device__ __forceinline__ unsigned cvt_pk_bf16(float lo, float hi) { unsigned r; asm volatile("v_cvt_pk_bf16_f32 %0, %1, %2" : "=v"(r) : "v"(lo), "v"(hi)); return r; }
;     __device__ __forceinline__ void operator()(Acc& acc, const Unit& u, int wr, int wc, int fr, int fq, LAS unsigned char*, const LAS float* rst) const {
;     ...
;                     for (int n = 0; n < 2; ++n) { const f32x4 v = acc[ai][bj][m][n] * rs; const int cc = cc0 + bj * 128 + n * 16;
;                         *(f32x4*)(dst + (size_t)row * 1024 + cc) = v;
;                         if (!isV) { u32x2 w; w.x = cvt_pk_bf16(v[0], v[1]); w.y = cvt_pk_bf16(v[2], v[3]); *(u32x2*)(Kb + ((size_t)l * 2048 + row) * 1024 + cc) = w; }
;                         else { u32x2 w; w.x = cvt_pk_bf16(v[0], v[1]); w.y = cvt_pk_bf16(v[2], v[3]); *(u32x2*)(Vt + ((size_t)l * 2048 + row) * 1024 + cc) = w; } }
.LBB0_206:
	s_lshl_b64 s[22:23], s[22:23], 11
	v_lshl_add_u64 v[124:125], s[22:23], 0, v[138:139]
	s_add_u32 s0, s50, s0
	v_lshlrev_b64 v[126:127], 11, v[124:125]
	s_addc_u32 s1, s51, s1
	v_lshl_add_u64 v[156:157], s[0:1], 0, v[126:127]
	v_lshlrev_b32_e32 v124, 1, v155
	v_mov_b32_e32 v125, v133
	v_lshl_add_u64 v[156:157], v[156:157], 0, v[124:125]
	v_mov_b32_e32 v143, v142
	global_store_dwordx2 v[156:157], v[146:147], off
	v_mov_b32_e32 v146, v142
	v_mov_b32_e32 v147, v142
	v_cndmask_b32_e64 v125, 0, 1, s[10:11]
	v_pk_mul_f32 v[122:123], v[122:123], v[146:147]
	v_pk_mul_f32 v[120:121], v[120:121], v[142:143]
	v_cmp_ne_u32_e64 s[0:1], 1, v125
	s_andn2_b64 vcc, exec, s[10:11]
	s_mov_b64 s[10:11], -1
	global_store_dwordx4 v[144:145], v[120:123], off offset:64 sc1
	s_cbranch_vccnz .LBB0_208
	s_mov_b64 s[10:11], 0
	v_cvt_pk_bf16_f32 v146, v120, v121
	v_cvt_pk_bf16_f32 v147, v122, v123

; __device__ __forceinline__ unsigned cvt_pk_bf16(float lo, float hi) { unsigned r; asm volatile("v_cvt_pk_bf16_f32 %0, %1, %2" : "=v"(r) : "v"(lo), "v"(hi)); return r; }
;     __device__ __forceinline__ void operator()(Acc& acc, const Unit& u, int wr, int wc, int fr, int fq, LAS unsigned char*, const LAS float* rst) const {
;     ...
;                     for (int n = 0; n < 2; ++n) { const f32x4 v = acc[ai][bj][m][n] * rs; const int cc = cc0 + bj * 128 + n * 16;
;                         *(f32x4*)(dst + (size_t)row * 1024 + cc) = v;
;                         if (!isV) { u32x2 w; w.x = cvt_pk_bf16(v[0], v[1]); w.y = cvt_pk_bf16(v[2], v[3]); *(u32x2*)(Kb + ((size_t)l * 2048 + row) * 1024 + cc) = w; }
;                         else { u32x2 w; w.x = cvt_pk_bf16(v[0], v[1]); w.y = cvt_pk_bf16(v[2], v[3]); *(u32x2*)(Vt + ((size_t)l * 2048 + row) * 1024 + cc) = w; } }
.LBB0_210:
	s_add_u32 s10, s50, s10
	s_addc_u32 s11, s51, s11
	v_lshl_add_u64 v[120:121], s[10:11], 0, v[126:127]
	v_mov_b32_e32 v125, v133
	v_lshl_add_u64 v[120:121], v[120:121], 0, v[124:125]
	global_store_dwordx2 v[120:121], v[146:147], off offset:32
	v_mov_b32_e32 v120, v142
	v_mov_b32_e32 v121, v142
	v_pk_mul_f32 v[118:119], v[118:119], v[120:121]
	v_pk_mul_f32 v[116:117], v[116:117], v[142:143]
	s_and_b64 vcc, exec, s[0:1]
	s_mov_b64 s[10:11], -1
	global_store_dwordx4 v[144:145], v[116:119], off offset:512 sc1
	s_cbranch_vccnz .LBB0_212
	s_mov_b64 s[10:11], 0
	v_cvt_pk_bf16_f32 v120, v116, v117
	v_cvt_pk_bf16_f32 v121, v118, v119

; __device__ __forceinline__ unsigned cvt_pk_bf16(float lo, float hi) { unsigned r; asm volatile("v_cvt_pk_bf16_f32 %0, %1, %2" : "=v"(r) : "v"(lo), "v"(hi)); return r; }
;     __device__ __forceinline__ void operator()(Acc& acc, const Unit& u, int wr, int wc, int fr, int fq, LAS unsigned char*, const LAS float* rst) const {
;     ...
;                     for (int n = 0; n < 2; ++n) { const f32x4 v = acc[ai][bj][m][n] * rs; const int cc = cc0 + bj * 128 + n * 16;
;                         *(f32x4*)(dst + (size_t)row * 1024 + cc) = v;
;                         if (!isV) { u32x2 w; w.x = cvt_pk_bf16(v[0], v[1]); w.y = cvt_pk_bf16(v[2], v[3]); *(u32x2*)(Kb + ((size_t)l * 2048 + row) * 1024 + cc) = w; }
;                         else { u32x2 w; w.x = cvt_pk_bf16(v[0], v[1]); w.y = cvt_pk_bf16(v[2], v[3]); *(u32x2*)(Vt + ((size_t)l * 2048 + row) * 1024 + cc) = w; } }
.LBB0_214:
	s_add_u32 s10, s50, s10
	s_addc_u32 s11, s51, s11
	v_lshl_add_u64 v[116:117], s[10:11], 0, v[126:127]
	v_mov_b32_e32 v125, v133
	v_lshl_add_u64 v[116:117], v[116:117], 0, v[124:125]
	global_store_dwordx2 v[116:117], v[120:121], off offset:256
	v_mov_b32_e32 v116, v142
	v_mov_b32_e32 v117, v142
	v_pk_mul_f32 v[114:115], v[114:115], v[116:117]
	v_pk_mul_f32 v[112:113], v[112:113], v[142:143]
	s_and_b64 vcc, exec, s[0:1]
	s_mov_b64 s[10:11], -1
	global_store_dwordx4 v[144:145], v[112:115], off offset:576 sc1
	s_cbranch_vccnz .LBB0_216
	s_mov_b64 s[10:11], 0
	v_cvt_pk_bf16_f32 v116, v112, v113
	v_cvt_pk_bf16_f32 v117, v114, v115

; __device__ __forceinline__ unsigned cvt_pk_bf16(float lo, float hi) { unsigned r; asm volatile("v_cvt_pk_bf16_f32 %0, %1, %2" : "=v"(r) : "v"(lo), "v"(hi)); return r; }
;     __device__ __forceinline__ void operator()(Acc& acc, const Unit& u, int wr, int wc, int fr, int fq, LAS unsigned char*, const LAS float* rst) const {
;     ...
;                     for (int n = 0; n < 2; ++n) { const f32x4 v = acc[ai][bj][m][n] * rs; const int cc = cc0 + bj * 128 + n * 16;
;                         *(f32x4*)(dst + (size_t)row * 1024 + cc) = v;
;                         if (!isV) { u32x2 w; w.x = cvt_pk_bf16(v[0], v[1]); w.y = cvt_pk_bf16(v[2], v[3]); *(u32x2*)(Kb + ((size_t)l * 2048 + row) * 1024 + cc) = w; }
;                         else { u32x2 w; w.x = cvt_pk_bf16(v[0], v[1]); w.y = cvt_pk_bf16(v[2], v[3]); *(u32x2*)(Vt + ((size_t)l * 2048 + row) * 1024 + cc) = w; } }
.LBB0_218:
	s_add_u32 s10, s50, s10
	s_addc_u32 s11, s51, s11
	v_lshl_add_u64 v[112:113], s[10:11], 0, v[126:127]
	v_mov_b32_e32 v125, v133
	v_lshl_add_u64 v[112:113], v[112:113], 0, v[124:125]
	global_store_dwordx2 v[112:113], v[116:117], off offset:288
	v_or_b32_e32 v116, 16, v138
	v_ashrrev_i32_e32 v117, 31, v116
	v_lshl_add_u64 v[112:113], v[116:117], 2, s[6:7]
	v_mov_b32_e32 v112, v240
	v_lshlrev_b64 v[114:115], 12, v[116:117]
	v_lshl_add_u64 v[114:115], s[20:21], 0, v[114:115]
	s_and_b64 vcc, exec, s[0:1]
	v_lshl_add_u64 v[114:115], v[114:115], 0, v[132:133]
	s_mov_b64 s[10:11], -1
	s_nop 0
	v_pk_mul_f32 v[110:111], v[110:111], v[112:113] op_sel_hi:[1,0]
	v_pk_mul_f32 v[108:109], v[108:109], v[112:113] op_sel_hi:[1,0]
	global_store_dwordx4 v[114:115], v[108:111], off sc1
	s_cbranch_vccnz .LBB0_220
	s_mov_b64 s[10:11], 0
	v_cvt_pk_bf16_f32 v118, v108, v109
	v_cvt_pk_bf16_f32 v119, v110, v111

; __device__ __forceinline__ unsigned cvt_pk_bf16(float lo, float hi) { unsigned r; asm volatile("v_cvt_pk_bf16_f32 %0, %1, %2" : "=v"(r) : "v"(lo), "v"(hi)); return r; }
;     __device__ __forceinline__ void operator()(Acc& acc, const Unit& u, int wr, int wc, int fr, int fq, LAS unsigned char*, const LAS float* rst) const {
;     ...
;                     for (int n = 0; n < 2; ++n) { const f32x4 v = acc[ai][bj][m][n] * rs; const int cc = cc0 + bj * 128 + n * 16;
;                         *(f32x4*)(dst + (size_t)row * 1024 + cc) = v;
;                         if (!isV) { u32x2 w; w.x = cvt_pk_bf16(v[0], v[1]); w.y = cvt_pk_bf16(v[2], v[3]); *(u32x2*)(Kb + ((size_t)l * 2048 + row) * 1024 + cc) = w; }
;                         else { u32x2 w; w.x = cvt_pk_bf16(v[0], v[1]); w.y = cvt_pk_bf16(v[2], v[3]); *(u32x2*)(Vt + ((size_t)l * 2048 + row) * 1024 + cc) = w; } }
.LBB0_222:
	v_lshl_add_u64 v[108:109], s[22:23], 0, v[116:117]
	s_add_u32 s10, s50, s10
	v_lshlrev_b64 v[108:109], 11, v[108:109]
	s_addc_u32 s11, s51, s11
	v_lshl_add_u64 v[110:111], s[10:11], 0, v[108:109]
	v_mov_b32_e32 v125, v133
	v_lshl_add_u64 v[110:111], v[110:111], 0, v[124:125]
	v_mov_b32_e32 v113, v112
	global_store_dwordx2 v[110:111], v[118:119], off
	v_mov_b32_e32 v110, v112
	v_mov_b32_e32 v111, v112
	v_pk_mul_f32 v[106:107], v[106:107], v[110:111]
	v_pk_mul_f32 v[104:105], v[104:105], v[112:113]
	s_and_b64 vcc, exec, s[0:1]
	s_mov_b64 s[10:11], -1
	global_store_dwordx4 v[114:115], v[104:107], off offset:64 sc1
	s_cbranch_vccnz .LBB0_224
	s_mov_b64 s[10:11], 0
	v_cvt_pk_bf16_f32 v110, v104, v105
	v_cvt_pk_bf16_f32 v111, v106, v107

; __device__ __forceinline__ unsigned cvt_pk_bf16(float lo, float hi) { unsigned r; asm volatile("v_cvt_pk_bf16_f32 %0, %1, %2" : "=v"(r) : "v"(lo), "v"(hi)); return r; }
;     __device__ __forceinline__ void operator()(Acc& acc, const Unit& u, int wr, int wc, int fr, int fq, LAS unsigned char*, const LAS float* rst) const {
;     ...
;                     for (int n = 0; n < 2; ++n) { const f32x4 v = acc[ai][bj][m][n] * rs; const int cc = cc0 + bj * 128 + n * 16;
;                         *(f32x4*)(dst + (size_t)row * 1024 + cc) = v;
;                         if (!isV) { u32x2 w; w.x = cvt_pk_bf16(v[0], v[1]); w.y = cvt_pk_bf16(v[2], v[3]); *(u32x2*)(Kb + ((size_t)l * 2048 + row) * 1024 + cc) = w; }
;                         else { u32x2 w; w.x = cvt_pk_bf16(v[0], v[1]); w.y = cvt_pk_bf16(v[2], v[3]); *(u32x2*)(Vt + ((size_t)l * 2048 + row) * 1024 + cc) = w; } }
.LBB0_226:
	s_add_u32 s10, s50, s10
	s_addc_u32 s11, s51, s11
	v_lshl_add_u64 v[104:105], s[10:11], 0, v[108:109]
	v_mov_b32_e32 v125, v133
	v_lshl_add_u64 v[104:105], v[104:105], 0, v[124:125]
	global_store_dwordx2 v[104:105], v[110:111], off offset:32
	v_mov_b32_e32 v104, v112
	v_mov_b32_e32 v105, v112
	v_pk_mul_f32 v[102:103], v[102:103], v[104:105]
	v_pk_mul_f32 v[100:101], v[100:101], v[112:113]
	s_and_b64 vcc, exec, s[0:1]
	s_mov_b64 s[10:11], -1
	global_store_dwordx4 v[114:115], v[100:103], off offset:512 sc1
	s_cbranch_vccnz .LBB0_228
	s_mov_b64 s[10:11], 0
	v_cvt_pk_bf16_f32 v104, v100, v101
	v_cvt_pk_bf16_f32 v105, v102, v103

; __device__ __forceinline__ unsigned cvt_pk_bf16(float lo, float hi) { unsigned r; asm volatile("v_cvt_pk_bf16_f32 %0, %1, %2" : "=v"(r) : "v"(lo), "v"(hi)); return r; }
;     __device__ __forceinline__ void operator()(Acc& acc, const Unit& u, int wr, int wc, int fr, int fq, LAS unsigned char*, const LAS float* rst) const {
;     ...
;                     for (int n = 0; n < 2; ++n) { const f32x4 v = acc[ai][bj][m][n] * rs; const int cc = cc0 + bj * 128 + n * 16;
;                         *(f32x4*)(dst + (size_t)row * 1024 + cc) = v;
;                         if (!isV) { u32x2 w; w.x = cvt_pk_bf16(v[0], v[1]); w.y = cvt_pk_bf16(v[2], v[3]); *(u32x2*)(Kb + ((size_t)l * 2048 + row) * 1024 + cc) = w; }
;                         else { u32x2 w; w.x = cvt_pk_bf16(v[0], v[1]); w.y = cvt_pk_bf16(v[2], v[3]); *(u32x2*)(Vt + ((size_t)l * 2048 + row) * 1024 + cc) = w; } }
.LBB0_230:
	s_add_u32 s10, s50, s10
	s_addc_u32 s11, s51, s11
	v_lshl_add_u64 v[100:101], s[10:11], 0, v[108:109]
	v_mov_b32_e32 v125, v133
	v_lshl_add_u64 v[100:101], v[100:101], 0, v[124:125]
	global_store_dwordx2 v[100:101], v[104:105], off offset:256
	v_mov_b32_e32 v100, v112
	v_mov_b32_e32 v101, v112
	v_pk_mul_f32 v[98:99], v[98:99], v[100:101]
	v_pk_mul_f32 v[96:97], v[96:97], v[112:113]
	s_and_b64 vcc, exec, s[0:1]
	s_mov_b64 s[10:11], -1
	global_store_dwordx4 v[114:115], v[96:99], off offset:576 sc1
	s_cbranch_vccnz .LBB0_232
	s_mov_b64 s[10:11], 0
	v_cvt_pk_bf16_f32 v100, v96, v97
	v_cvt_pk_bf16_f32 v101, v98, v99

; __device__ __forceinline__ unsigned cvt_pk_bf16(float lo, float hi) { unsigned r; asm volatile("v_cvt_pk_bf16_f32 %0, %1, %2" : "=v"(r) : "v"(lo), "v"(hi)); return r; }
;     __device__ __forceinline__ void operator()(Acc& acc, const Unit& u, int wr, int wc, int fr, int fq, LAS unsigned char*, const LAS float* rst) const {
;     ...
;                     for (int n = 0; n < 2; ++n) { const f32x4 v = acc[ai][bj][m][n] * rs; const int cc = cc0 + bj * 128 + n * 16;
;                         *(f32x4*)(dst + (size_t)row * 1024 + cc) = v;
;                         if (!isV) { u32x2 w; w.x = cvt_pk_bf16(v[0], v[1]); w.y = cvt_pk_bf16(v[2], v[3]); *(u32x2*)(Kb + ((size_t)l * 2048 + row) * 1024 + cc) = w; }
;                         else { u32x2 w; w.x = cvt_pk_bf16(v[0], v[1]); w.y = cvt_pk_bf16(v[2], v[3]); *(u32x2*)(Vt + ((size_t)l * 2048 + row) * 1024 + cc) = w; } }
.LBB0_234:
	s_add_u32 s10, s50, s10
	s_addc_u32 s11, s51, s11
	v_lshl_add_u64 v[96:97], s[10:11], 0, v[108:109]
	v_mov_b32_e32 v125, v133
	v_lshl_add_u64 v[96:97], v[96:97], 0, v[124:125]
	global_store_dwordx2 v[96:97], v[100:101], off offset:288
	v_or_b32_e32 v100, 32, v138
	v_ashrrev_i32_e32 v101, 31, v100
	v_lshl_add_u64 v[96:97], v[100:101], 2, s[6:7]
	v_mov_b32_e32 v96, v241
	v_lshlrev_b64 v[98:99], 12, v[100:101]
	v_lshl_add_u64 v[98:99], s[20:21], 0, v[98:99]
	s_and_b64 vcc, exec, s[0:1]
	v_lshl_add_u64 v[98:99], v[98:99], 0, v[132:133]
	s_mov_b64 s[10:11], -1
	s_nop 0
	v_pk_mul_f32 v[94:95], v[94:95], v[96:97] op_sel_hi:[1,0]
	v_pk_mul_f32 v[92:93], v[92:93], v[96:97] op_sel_hi:[1,0]
	global_store_dwordx4 v[98:99], v[92:95], off sc1
	s_cbranch_vccnz .LBB0_236
	s_mov_b64 s[10:11], 0
	v_cvt_pk_bf16_f32 v102, v92, v93
	v_cvt_pk_bf16_f32 v103, v94, v95

; __device__ __forceinline__ unsigned cvt_pk_bf16(float lo, float hi) { unsigned r; asm volatile("v_cvt_pk_bf16_f32 %0, %1, %2" : "=v"(r) : "v"(lo), "v"(hi)); return r; }
;     __device__ __forceinline__ void operator()(Acc& acc, const Unit& u, int wr, int wc, int fr, int fq, LAS unsigned char*, const LAS float* rst) const {
;     ...
;                     for (int n = 0; n < 2; ++n) { const f32x4 v = acc[ai][bj][m][n] * rs; const int cc = cc0 + bj * 128 + n * 16;
;                         *(f32x4*)(dst + (size_t)row * 1024 + cc) = v;
;                         if (!isV) { u32x2 w; w.x = cvt_pk_bf16(v[0], v[1]); w.y = cvt_pk_bf16(v[2], v[3]); *(u32x2*)(Kb + ((size_t)l * 2048 + row) * 1024 + cc) = w; }
;                         else { u32x2 w; w.x = cvt_pk_bf16(v[0], v[1]); w.y = cvt_pk_bf16(v[2], v[3]); *(u32x2*)(Vt + ((size_t)l * 2048 + row) * 1024 + cc) = w; } }
.LBB0_238:
	v_lshl_add_u64 v[92:93], s[22:23], 0, v[100:101]
	s_add_u32 s10, s50, s10
	v_lshlrev_b64 v[92:93], 11, v[92:93]
	s_addc_u32 s11, s51, s11
	v_lshl_add_u64 v[94:95], s[10:11], 0, v[92:93]
	v_mov_b32_e32 v125, v133
	v_lshl_add_u64 v[94:95], v[94:95], 0, v[124:125]
	v_mov_b32_e32 v97, v96
	global_store_dwordx2 v[94:95], v[102:103], off
	v_mov_b32_e32 v94, v96
	v_mov_b32_e32 v95, v96
	v_pk_mul_f32 v[90:91], v[90:91], v[94:95]
	v_pk_mul_f32 v[88:89], v[88:89], v[96:97]
	s_and_b64 vcc, exec, s[0:1]
	s_mov_b64 s[10:11], -1
	global_store_dwordx4 v[98:99], v[88:91], off offset:64 sc1
	s_cbranch_vccnz .LBB0_240
	s_mov_b64 s[10:11], 0
	v_cvt_pk_bf16_f32 v94, v88, v89
	v_cvt_pk_bf16_f32 v95, v90, v91

; __device__ __forceinline__ unsigned cvt_pk_bf16(float lo, float hi) { unsigned r; asm volatile("v_cvt_pk_bf16_f32 %0, %1, %2" : "=v"(r) : "v"(lo), "v"(hi)); return r; }
;     __device__ __forceinline__ void operator()(Acc& acc, const Unit& u, int wr, int wc, int fr, int fq, LAS unsigned char*, const LAS float* rst) const {
;     ...
;                     for (int n = 0; n < 2; ++n) { const f32x4 v = acc[ai][bj][m][n] * rs; const int cc = cc0 + bj * 128 + n * 16;
;                         *(f32x4*)(dst + (size_t)row * 1024 + cc) = v;
;                         if (!isV) { u32x2 w; w.x = cvt_pk_bf16(v[0], v[1]); w.y = cvt_pk_bf16(v[2], v[3]); *(u32x2*)(Kb + ((size_t)l * 2048 + row) * 1024 + cc) = w; }
;                         else { u32x2 w; w.x = cvt_pk_bf16(v[0], v[1]); w.y = cvt_pk_bf16(v[2], v[3]); *(u32x2*)(Vt + ((size_t)l * 2048 + row) * 1024 + cc) = w; } }
.LBB0_242:
	s_add_u32 s10, s50, s10
	s_addc_u32 s11, s51, s11
	v_lshl_add_u64 v[88:89], s[10:11], 0, v[92:93]
	v_mov_b32_e32 v125, v133
	v_lshl_add_u64 v[88:89], v[88:89], 0, v[124:125]
	global_store_dwordx2 v[88:89], v[94:95], off offset:32
	v_mov_b32_e32 v88, v96
	v_mov_b32_e32 v89, v96
	v_pk_mul_f32 v[86:87], v[86:87], v[88:89]
	v_pk_mul_f32 v[84:85], v[84:85], v[96:97]
	s_and_b64 vcc, exec, s[0:1]
	s_mov_b64 s[10:11], -1
	global_store_dwordx4 v[98:99], v[84:87], off offset:512 sc1
	s_cbranch_vccnz .LBB0_244
	s_mov_b64 s[10:11], 0
	v_cvt_pk_bf16_f32 v88, v84, v85
	v_cvt_pk_bf16_f32 v89, v86, v87

; __device__ __forceinline__ unsigned cvt_pk_bf16(float lo, float hi) { unsigned r; asm volatile("v_cvt_pk_bf16_f32 %0, %1, %2" : "=v"(r) : "v"(lo), "v"(hi)); return r; }
;     __device__ __forceinline__ void operator()(Acc& acc, const Unit& u, int wr, int wc, int fr, int fq, LAS unsigned char*, const LAS float* rst) const {
;     ...
;                     for (int n = 0; n < 2; ++n) { const f32x4 v = acc[ai][bj][m][n] * rs; const int cc = cc0 + bj * 128 + n * 16;
;                         *(f32x4*)(dst + (size_t)row * 1024 + cc) = v;
;                         if (!isV) { u32x2 w; w.x = cvt_pk_bf16(v[0], v[1]); w.y = cvt_pk_bf16(v[2], v[3]); *(u32x2*)(Kb + ((size_t)l * 2048 + row) * 1024 + cc) = w; }
;                         else { u32x2 w; w.x = cvt_pk_bf16(v[0], v[1]); w.y = cvt_pk_bf16(v[2], v[3]); *(u32x2*)(Vt + ((size_t)l * 2048 + row) * 1024 + cc) = w; } }
.LBB0_246:
	s_add_u32 s10, s50, s10
	s_addc_u32 s11, s51, s11
	v_lshl_add_u64 v[84:85], s[10:11], 0, v[92:93]
	v_mov_b32_e32 v125, v133
	v_lshl_add_u64 v[84:85], v[84:85], 0, v[124:125]
	global_store_dwordx2 v[84:85], v[88:89], off offset:256
	v_mov_b32_e32 v84, v96
	v_mov_b32_e32 v85, v96
	v_pk_mul_f32 v[82:83], v[82:83], v[84:85]
	v_pk_mul_f32 v[80:81], v[80:81], v[96:97]
	s_and_b64 vcc, exec, s[0:1]
	s_mov_b64 s[10:11], -1
	global_store_dwordx4 v[98:99], v[80:83], off offset:576 sc1
	s_cbranch_vccnz .LBB0_248
	s_mov_b64 s[10:11], 0
	v_cvt_pk_bf16_f32 v84, v80, v81
	v_cvt_pk_bf16_f32 v85, v82, v83

; __device__ __forceinline__ unsigned cvt_pk_bf16(float lo, float hi) { unsigned r; asm volatile("v_cvt_pk_bf16_f32 %0, %1, %2" : "=v"(r) : "v"(lo), "v"(hi)); return r; }
;     __device__ __forceinline__ void operator()(Acc& acc, const Unit& u, int wr, int wc, int fr, int fq, LAS unsigned char*, const LAS float* rst) const {
;     ...
;                     for (int n = 0; n < 2; ++n) { const f32x4 v = acc[ai][bj][m][n] * rs; const int cc = cc0 + bj * 128 + n * 16;
;                         *(f32x4*)(dst + (size_t)row * 1024 + cc) = v;
;                         if (!isV) { u32x2 w; w.x = cvt_pk_bf16(v[0], v[1]); w.y = cvt_pk_bf16(v[2], v[3]); *(u32x2*)(Kb + ((size_t)l * 2048 + row) * 1024 + cc) = w; }
;                         else { u32x2 w; w.x = cvt_pk_bf16(v[0], v[1]); w.y = cvt_pk_bf16(v[2], v[3]); *(u32x2*)(Vt + ((size_t)l * 2048 + row) * 1024 + cc) = w; } }
.LBB0_250:
	s_add_u32 s10, s50, s10
	s_addc_u32 s11, s51, s11
	v_lshl_add_u64 v[80:81], s[10:11], 0, v[92:93]
	v_mov_b32_e32 v125, v133
	v_lshl_add_u64 v[80:81], v[80:81], 0, v[124:125]
	global_store_dwordx2 v[80:81], v[84:85], off offset:288
	v_or_b32_e32 v84, 48, v138
	v_ashrrev_i32_e32 v85, 31, v84
	v_lshl_add_u64 v[80:81], v[84:85], 2, s[6:7]
	v_mov_b32_e32 v80, v242
	v_lshlrev_b64 v[82:83], 12, v[84:85]
	v_lshl_add_u64 v[82:83], s[20:21], 0, v[82:83]
	s_and_b64 vcc, exec, s[0:1]
	v_lshl_add_u64 v[82:83], v[82:83], 0, v[132:133]
	s_mov_b64 s[10:11], -1
	s_nop 0
	v_pk_mul_f32 v[78:79], v[78:79], v[80:81] op_sel_hi:[1,0]
	v_pk_mul_f32 v[76:77], v[76:77], v[80:81] op_sel_hi:[1,0]
	global_store_dwordx4 v[82:83], v[76:79], off sc1
	s_cbranch_vccnz .LBB0_252
	s_mov_b64 s[10:11], 0
	v_cvt_pk_bf16_f32 v86, v76, v77
	v_cvt_pk_bf16_f32 v87, v78, v79

; __device__ __forceinline__ unsigned cvt_pk_bf16(float lo, float hi) { unsigned r; asm volatile("v_cvt_pk_bf16_f32 %0, %1, %2" : "=v"(r) : "v"(lo), "v"(hi)); return r; }
;     __device__ __forceinline__ void operator()(Acc& acc, const Unit& u, int wr, int wc, int fr, int fq, LAS unsigned char*, const LAS float* rst) const {
;     ...
;                     for (int n = 0; n < 2; ++n) { const f32x4 v = acc[ai][bj][m][n] * rs; const int cc = cc0 + bj * 128 + n * 16;
;                         *(f32x4*)(dst + (size_t)row * 1024 + cc) = v;
;                         if (!isV) { u32x2 w; w.x = cvt_pk_bf16(v[0], v[1]); w.y = cvt_pk_bf16(v[2], v[3]); *(u32x2*)(Kb + ((size_t)l * 2048 + row) * 1024 + cc) = w; }
;                         else { u32x2 w; w.x = cvt_pk_bf16(v[0], v[1]); w.y = cvt_pk_bf16(v[2], v[3]); *(u32x2*)(Vt + ((size_t)l * 2048 + row) * 1024 + cc) = w; } }
.LBB0_254:
	v_lshl_add_u64 v[76:77], s[22:23], 0, v[84:85]
	s_add_u32 s10, s50, s10
	v_lshlrev_b64 v[76:77], 11, v[76:77]
	s_addc_u32 s11, s51, s11
	v_lshl_add_u64 v[78:79], s[10:11], 0, v[76:77]
	v_mov_b32_e32 v125, v133
	v_lshl_add_u64 v[78:79], v[78:79], 0, v[124:125]
	v_mov_b32_e32 v81, v80
	global_store_dwordx2 v[78:79], v[86:87], off
	v_mov_b32_e32 v78, v80
	v_mov_b32_e32 v79, v80
	v_pk_mul_f32 v[74:75], v[74:75], v[78:79]
	v_pk_mul_f32 v[72:73], v[72:73], v[80:81]
	s_and_b64 vcc, exec, s[0:1]
	s_mov_b64 s[10:11], -1
	global_store_dwordx4 v[82:83], v[72:75], off offset:64 sc1
	s_cbranch_vccnz .LBB0_256
	s_mov_b64 s[10:11], 0
	v_cvt_pk_bf16_f32 v78, v72, v73
	v_cvt_pk_bf16_f32 v79, v74, v75

; __device__ __forceinline__ unsigned cvt_pk_bf16(float lo, float hi) { unsigned r; asm volatile("v_cvt_pk_bf16_f32 %0, %1, %2" : "=v"(r) : "v"(lo), "v"(hi)); return r; }
;     __device__ __forceinline__ void operator()(Acc& acc, const Unit& u, int wr, int wc, int fr, int fq, LAS unsigned char*, const LAS float* rst) const {
;     ...
;                     for (int n = 0; n < 2; ++n) { const f32x4 v = acc[ai][bj][m][n] * rs; const int cc = cc0 + bj * 128 + n * 16;
;                         *(f32x4*)(dst + (size_t)row * 1024 + cc) = v;
;                         if (!isV) { u32x2 w; w.x = cvt_pk_bf16(v[0], v[1]); w.y = cvt_pk_bf16(v[2], v[3]); *(u32x2*)(Kb + ((size_t)l * 2048 + row) * 1024 + cc) = w; }
;                         else { u32x2 w; w.x = cvt_pk_bf16(v[0], v[1]); w.y = cvt_pk_bf16(v[2], v[3]); *(u32x2*)(Vt + ((size_t)l * 2048 + row) * 1024 + cc) = w; } }
.LBB0_258:
	s_add_u32 s10, s50, s10
	s_addc_u32 s11, s51, s11
	v_lshl_add_u64 v[72:73], s[10:11], 0, v[76:77]
	v_mov_b32_e32 v125, v133
	v_lshl_add_u64 v[72:73], v[72:73], 0, v[124:125]
	global_store_dwordx2 v[72:73], v[78:79], off offset:32
	v_mov_b32_e32 v72, v80
	v_mov_b32_e32 v73, v80
	v_pk_mul_f32 v[70:71], v[70:71], v[72:73]
	v_pk_mul_f32 v[68:69], v[68:69], v[80:81]
	s_and_b64 vcc, exec, s[0:1]
	s_mov_b64 s[10:11], -1
	global_store_dwordx4 v[82:83], v[68:71], off offset:512 sc1
	s_cbranch_vccnz .LBB0_260
	s_mov_b64 s[10:11], 0
	v_cvt_pk_bf16_f32 v72, v68, v69
	v_cvt_pk_bf16_f32 v73, v70, v71

; __device__ __forceinline__ unsigned cvt_pk_bf16(float lo, float hi) { unsigned r; asm volatile("v_cvt_pk_bf16_f32 %0, %1, %2" : "=v"(r) : "v"(lo), "v"(hi)); return r; }
;     __device__ __forceinline__ void operator()(Acc& acc, const Unit& u, int wr, int wc, int fr, int fq, LAS unsigned char*, const LAS float* rst) const {
;     ...
;                     for (int n = 0; n < 2; ++n) { const f32x4 v = acc[ai][bj][m][n] * rs; const int cc = cc0 + bj * 128 + n * 16;
;                         *(f32x4*)(dst + (size_t)row * 1024 + cc) = v;
;                         if (!isV) { u32x2 w; w.x = cvt_pk_bf16(v[0], v[1]); w.y = cvt_pk_bf16(v[2], v[3]); *(u32x2*)(Kb + ((size_t)l * 2048 + row) * 1024 + cc) = w; }
;                         else { u32x2 w; w.x = cvt_pk_bf16(v[0], v[1]); w.y = cvt_pk_bf16(v[2], v[3]); *(u32x2*)(Vt + ((size_t)l * 2048 + row) * 1024 + cc) = w; } }
.LBB0_262:
	s_add_u32 s10, s50, s10
	s_addc_u32 s11, s51, s11
	v_lshl_add_u64 v[68:69], s[10:11], 0, v[76:77]
	v_mov_b32_e32 v125, v133
	v_lshl_add_u64 v[68:69], v[68:69], 0, v[124:125]
	global_store_dwordx2 v[68:69], v[72:73], off offset:256
	v_mov_b32_e32 v68, v80
	v_mov_b32_e32 v69, v80
	v_pk_mul_f32 v[66:67], v[66:67], v[68:69]
	v_pk_mul_f32 v[64:65], v[64:65], v[80:81]
	s_and_b64 vcc, exec, s[0:1]
	s_mov_b64 s[10:11], -1
	global_store_dwordx4 v[82:83], v[64:67], off offset:576 sc1
	s_cbranch_vccnz .LBB0_264
	s_mov_b64 s[10:11], 0
	v_cvt_pk_bf16_f32 v68, v64, v65
	v_cvt_pk_bf16_f32 v69, v66, v67

; __device__ __forceinline__ unsigned cvt_pk_bf16(float lo, float hi) { unsigned r; asm volatile("v_cvt_pk_bf16_f32 %0, %1, %2" : "=v"(r) : "v"(lo), "v"(hi)); return r; }
;     __device__ __forceinline__ void operator()(Acc& acc, const Unit& u, int wr, int wc, int fr, int fq, LAS unsigned char*, const LAS float* rst) const {
;     ...
;                     for (int n = 0; n < 2; ++n) { const f32x4 v = acc[ai][bj][m][n] * rs; const int cc = cc0 + bj * 128 + n * 16;
;                         *(f32x4*)(dst + (size_t)row * 1024 + cc) = v;
;                         if (!isV) { u32x2 w; w.x = cvt_pk_bf16(v[0], v[1]); w.y = cvt_pk_bf16(v[2], v[3]); *(u32x2*)(Kb + ((size_t)l * 2048 + row) * 1024 + cc) = w; }
;                         else { u32x2 w; w.x = cvt_pk_bf16(v[0], v[1]); w.y = cvt_pk_bf16(v[2], v[3]); *(u32x2*)(Vt + ((size_t)l * 2048 + row) * 1024 + cc) = w; } }
.LBB0_266:
	s_add_u32 s10, s50, s10
	s_addc_u32 s11, s51, s11
	v_lshl_add_u64 v[64:65], s[10:11], 0, v[76:77]
	v_mov_b32_e32 v125, v133
	v_lshl_add_u64 v[64:65], v[64:65], 0, v[124:125]
	global_store_dwordx2 v[64:65], v[68:69], off offset:288
	v_mov_b32_e32 v64, v243
	v_add_u32_e32 v68, 0x80, v138
	v_ashrrev_i32_e32 v69, 31, v68
	v_lshlrev_b64 v[66:67], 12, v[68:69]
	v_lshl_add_u64 v[66:67], s[20:21], 0, v[66:67]
	s_and_b64 vcc, exec, s[0:1]
	v_lshl_add_u64 v[66:67], v[66:67], 0, v[132:133]
	s_mov_b64 s[10:11], -1
	s_nop 0
	v_pk_mul_f32 v[62:63], v[62:63], v[64:65] op_sel_hi:[1,0]
	v_pk_mul_f32 v[60:61], v[60:61], v[64:65] op_sel_hi:[1,0]
	global_store_dwordx4 v[66:67], v[60:63], off sc1
	s_cbranch_vccnz .LBB0_268
	s_mov_b64 s[10:11], 0
	v_cvt_pk_bf16_f32 v70, v60, v61
	v_cvt_pk_bf16_f32 v71, v62, v63

; __device__ __forceinline__ unsigned cvt_pk_bf16(float lo, float hi) { unsigned r; asm volatile("v_cvt_pk_bf16_f32 %0, %1, %2" : "=v"(r) : "v"(lo), "v"(hi)); return r; }
;     __device__ __forceinline__ void operator()(Acc& acc, const Unit& u, int wr, int wc, int fr, int fq, LAS unsigned char*, const LAS float* rst) const {
;     ...
;                     for (int n = 0; n < 2; ++n) { const f32x4 v = acc[ai][bj][m][n] * rs; const int cc = cc0 + bj * 128 + n * 16;
;                         *(f32x4*)(dst + (size_t)row * 1024 + cc) = v;
;                         if (!isV) { u32x2 w; w.x = cvt_pk_bf16(v[0], v[1]); w.y = cvt_pk_bf16(v[2], v[3]); *(u32x2*)(Kb + ((size_t)l * 2048 + row) * 1024 + cc) = w; }
;                         else { u32x2 w; w.x = cvt_pk_bf16(v[0], v[1]); w.y = cvt_pk_bf16(v[2], v[3]); *(u32x2*)(Vt + ((size_t)l * 2048 + row) * 1024 + cc) = w; } }
.LBB0_270:
	v_lshl_add_u64 v[60:61], s[22:23], 0, v[68:69]
	s_add_u32 s10, s50, s10
	v_lshlrev_b64 v[60:61], 11, v[60:61]
	s_addc_u32 s11, s51, s11
	v_lshl_add_u64 v[62:63], s[10:11], 0, v[60:61]
	v_mov_b32_e32 v125, v133
	v_lshl_add_u64 v[62:63], v[62:63], 0, v[124:125]
	v_mov_b32_e32 v65, v64
	global_store_dwordx2 v[62:63], v[70:71], off
	v_mov_b32_e32 v62, v64
	v_mov_b32_e32 v63, v64
	v_pk_mul_f32 v[58:59], v[58:59], v[62:63]
	v_pk_mul_f32 v[56:57], v[56:57], v[64:65]
	s_and_b64 vcc, exec, s[0:1]
	s_mov_b64 s[10:11], -1
	global_store_dwordx4 v[66:67], v[56:59], off offset:64 sc1
	s_cbranch_vccnz .LBB0_272
	s_mov_b64 s[10:11], 0
	v_cvt_pk_bf16_f32 v62, v56, v57
	v_cvt_pk_bf16_f32 v63, v58, v59

; __device__ __forceinline__ unsigned cvt_pk_bf16(float lo, float hi) { unsigned r; asm volatile("v_cvt_pk_bf16_f32 %0, %1, %2" : "=v"(r) : "v"(lo), "v"(hi)); return r; }
;     __device__ __forceinline__ void operator()(Acc& acc, const Unit& u, int wr, int wc, int fr, int fq, LAS unsigned char*, const LAS float* rst) const {
;     ...
;                     for (int n = 0; n < 2; ++n) { const f32x4 v = acc[ai][bj][m][n] * rs; const int cc = cc0 + bj * 128 + n * 16;
;                         *(f32x4*)(dst + (size_t)row * 1024 + cc) = v;
;                         if (!isV) { u32x2 w; w.x = cvt_pk_bf16(v[0], v[1]); w.y = cvt_pk_bf16(v[2], v[3]); *(u32x2*)(Kb + ((size_t)l * 2048 + row) * 1024 + cc) = w; }
;                         else { u32x2 w; w.x = cvt_pk_bf16(v[0], v[1]); w.y = cvt_pk_bf16(v[2], v[3]); *(u32x2*)(Vt + ((size_t)l * 2048 + row) * 1024 + cc) = w; } }
.LBB0_274:
	s_add_u32 s10, s50, s10
	s_addc_u32 s11, s51, s11
	v_lshl_add_u64 v[56:57], s[10:11], 0, v[60:61]
	v_mov_b32_e32 v125, v133
	v_lshl_add_u64 v[56:57], v[56:57], 0, v[124:125]
	global_store_dwordx2 v[56:57], v[62:63], off offset:32
	v_mov_b32_e32 v56, v64
	v_mov_b32_e32 v57, v64
	v_pk_mul_f32 v[54:55], v[54:55], v[56:57]
	v_pk_mul_f32 v[52:53], v[52:53], v[64:65]
	s_and_b64 vcc, exec, s[0:1]
	s_mov_b64 s[10:11], -1
	global_store_dwordx4 v[66:67], v[52:55], off offset:512 sc1
	s_cbranch_vccnz .LBB0_276
	s_mov_b64 s[10:11], 0
	v_cvt_pk_bf16_f32 v56, v52, v53
	v_cvt_pk_bf16_f32 v57, v54, v55

; __device__ __forceinline__ unsigned cvt_pk_bf16(float lo, float hi) { unsigned r; asm volatile("v_cvt_pk_bf16_f32 %0, %1, %2" : "=v"(r) : "v"(lo), "v"(hi)); return r; }
;     __device__ __forceinline__ void operator()(Acc& acc, const Unit& u, int wr, int wc, int fr, int fq, LAS unsigned char*, const LAS float* rst) const {
;     ...
;                     for (int n = 0; n < 2; ++n) { const f32x4 v = acc[ai][bj][m][n] * rs; const int cc = cc0 + bj * 128 + n * 16;
;                         *(f32x4*)(dst + (size_t)row * 1024 + cc) = v;
;                         if (!isV) { u32x2 w; w.x = cvt_pk_bf16(v[0], v[1]); w.y = cvt_pk_bf16(v[2], v[3]); *(u32x2*)(Kb + ((size_t)l * 2048 + row) * 1024 + cc) = w; }
;                         else { u32x2 w; w.x = cvt_pk_bf16(v[0], v[1]); w.y = cvt_pk_bf16(v[2], v[3]); *(u32x2*)(Vt + ((size_t)l * 2048 + row) * 1024 + cc) = w; } }
.LBB0_278:
	s_add_u32 s10, s50, s10
	s_addc_u32 s11, s51, s11
	v_lshl_add_u64 v[52:53], s[10:11], 0, v[60:61]
	v_mov_b32_e32 v125, v133
	v_lshl_add_u64 v[52:53], v[52:53], 0, v[124:125]
	global_store_dwordx2 v[52:53], v[56:57], off offset:256
	v_mov_b32_e32 v52, v64
	v_mov_b32_e32 v53, v64
	v_pk_mul_f32 v[50:51], v[50:51], v[52:53]
	v_pk_mul_f32 v[48:49], v[48:49], v[64:65]
	s_and_b64 vcc, exec, s[0:1]
	s_mov_b64 s[10:11], -1
	global_store_dwordx4 v[66:67], v[48:51], off offset:576 sc1
	s_cbranch_vccnz .LBB0_280
	s_mov_b64 s[10:11], 0
	v_cvt_pk_bf16_f32 v52, v48, v49
	v_cvt_pk_bf16_f32 v53, v50, v51

; __device__ __forceinline__ unsigned cvt_pk_bf16(float lo, float hi) { unsigned r; asm volatile("v_cvt_pk_bf16_f32 %0, %1, %2" : "=v"(r) : "v"(lo), "v"(hi)); return r; }
;     __device__ __forceinline__ void operator()(Acc& acc, const Unit& u, int wr, int wc, int fr, int fq, LAS unsigned char*, const LAS float* rst) const {
;     ...
;                     for (int n = 0; n < 2; ++n) { const f32x4 v = acc[ai][bj][m][n] * rs; const int cc = cc0 + bj * 128 + n * 16;
;                         *(f32x4*)(dst + (size_t)row * 1024 + cc) = v;
;                         if (!isV) { u32x2 w; w.x = cvt_pk_bf16(v[0], v[1]); w.y = cvt_pk_bf16(v[2], v[3]); *(u32x2*)(Kb + ((size_t)l * 2048 + row) * 1024 + cc) = w; }
;                         else { u32x2 w; w.x = cvt_pk_bf16(v[0], v[1]); w.y = cvt_pk_bf16(v[2], v[3]); *(u32x2*)(Vt + ((size_t)l * 2048 + row) * 1024 + cc) = w; } }
.LBB0_282:
	s_add_u32 s10, s50, s10
	s_addc_u32 s11, s51, s11
	v_lshl_add_u64 v[48:49], s[10:11], 0, v[60:61]
	v_mov_b32_e32 v125, v133
	v_lshl_add_u64 v[48:49], v[48:49], 0, v[124:125]
	global_store_dwordx2 v[48:49], v[52:53], off offset:288
	v_mov_b32_e32 v48, v244
	v_add_u32_e32 v52, 0x90, v138
	v_ashrrev_i32_e32 v53, 31, v52
	v_lshlrev_b64 v[50:51], 12, v[52:53]
	v_lshl_add_u64 v[50:51], s[20:21], 0, v[50:51]
	s_and_b64 vcc, exec, s[0:1]
	v_lshl_add_u64 v[50:51], v[50:51], 0, v[132:133]
	s_mov_b64 s[10:11], -1
	s_nop 0
	v_pk_mul_f32 v[46:47], v[46:47], v[48:49] op_sel_hi:[1,0]
	v_pk_mul_f32 v[44:45], v[44:45], v[48:49] op_sel_hi:[1,0]
	global_store_dwordx4 v[50:51], v[44:47], off sc1
	s_cbranch_vccnz .LBB0_284
	s_mov_b64 s[10:11], 0
	v_cvt_pk_bf16_f32 v54, v44, v45
	v_cvt_pk_bf16_f32 v55, v46, v47

; __device__ __forceinline__ unsigned cvt_pk_bf16(float lo, float hi) { unsigned r; asm volatile("v_cvt_pk_bf16_f32 %0, %1, %2" : "=v"(r) : "v"(lo), "v"(hi)); return r; }
;     __device__ __forceinline__ void operator()(Acc& acc, const Unit& u, int wr, int wc, int fr, int fq, LAS unsigned char*, const LAS float* rst) const {
;     ...
;                     for (int n = 0; n < 2; ++n) { const f32x4 v = acc[ai][bj][m][n] * rs; const int cc = cc0 + bj * 128 + n * 16;
;                         *(f32x4*)(dst + (size_t)row * 1024 + cc) = v;
;                         if (!isV) { u32x2 w; w.x = cvt_pk_bf16(v[0], v[1]); w.y = cvt_pk_bf16(v[2], v[3]); *(u32x2*)(Kb + ((size_t)l * 2048 + row) * 1024 + cc) = w; }
;                         else { u32x2 w; w.x = cvt_pk_bf16(v[0], v[1]); w.y = cvt_pk_bf16(v[2], v[3]); *(u32x2*)(Vt + ((size_t)l * 2048 + row) * 1024 + cc) = w; } }
.LBB0_286:
	v_lshl_add_u64 v[44:45], s[22:23], 0, v[52:53]
	s_add_u32 s10, s50, s10
	v_lshlrev_b64 v[44:45], 11, v[44:45]
	s_addc_u32 s11, s51, s11
	v_lshl_add_u64 v[46:47], s[10:11], 0, v[44:45]
	v_mov_b32_e32 v125, v133
	v_lshl_add_u64 v[46:47], v[46:47], 0, v[124:125]
	v_mov_b32_e32 v49, v48
	global_store_dwordx2 v[46:47], v[54:55], off
	v_mov_b32_e32 v46, v48
	v_mov_b32_e32 v47, v48
	v_pk_mul_f32 v[42:43], v[42:43], v[46:47]
	v_pk_mul_f32 v[40:41], v[40:41], v[48:49]
	s_and_b64 vcc, exec, s[0:1]
	s_mov_b64 s[10:11], -1
	global_store_dwordx4 v[50:51], v[40:43], off offset:64 sc1
	s_cbranch_vccnz .LBB0_288
	s_mov_b64 s[10:11], 0
	v_cvt_pk_bf16_f32 v46, v40, v41
	v_cvt_pk_bf16_f32 v47, v42, v43

; __device__ __forceinline__ unsigned cvt_pk_bf16(float lo, float hi) { unsigned r; asm volatile("v_cvt_pk_bf16_f32 %0, %1, %2" : "=v"(r) : "v"(lo), "v"(hi)); return r; }
;     __device__ __forceinline__ void operator()(Acc& acc, const Unit& u, int wr, int wc, int fr, int fq, LAS unsigned char*, const LAS float* rst) const {
;     ...
;                     for (int n = 0; n < 2; ++n) { const f32x4 v = acc[ai][bj][m][n] * rs; const int cc = cc0 + bj * 128 + n * 16;
;                         *(f32x4*)(dst + (size_t)row * 1024 + cc) = v;
;                         if (!isV) { u32x2 w; w.x = cvt_pk_bf16(v[0], v[1]); w.y = cvt_pk_bf16(v[2], v[3]); *(u32x2*)(Kb + ((size_t)l * 2048 + row) * 1024 + cc) = w; }
;                         else { u32x2 w; w.x = cvt_pk_bf16(v[0], v[1]); w.y = cvt_pk_bf16(v[2], v[3]); *(u32x2*)(Vt + ((size_t)l * 2048 + row) * 1024 + cc) = w; } }
.LBB0_290:
	s_add_u32 s10, s50, s10
	s_addc_u32 s11, s51, s11
	v_lshl_add_u64 v[40:41], s[10:11], 0, v[44:45]
	v_mov_b32_e32 v125, v133
	v_lshl_add_u64 v[40:41], v[40:41], 0, v[124:125]
	global_store_dwordx2 v[40:41], v[46:47], off offset:32
	v_mov_b32_e32 v40, v48
	v_mov_b32_e32 v41, v48
	v_pk_mul_f32 v[38:39], v[38:39], v[40:41]
	v_pk_mul_f32 v[36:37], v[36:37], v[48:49]
	s_and_b64 vcc, exec, s[0:1]
	s_mov_b64 s[10:11], -1
	global_store_dwordx4 v[50:51], v[36:39], off offset:512 sc1
	s_cbranch_vccnz .LBB0_292
	s_mov_b64 s[10:11], 0
	v_cvt_pk_bf16_f32 v40, v36, v37
	v_cvt_pk_bf16_f32 v41, v38, v39

; __device__ __forceinline__ unsigned cvt_pk_bf16(float lo, float hi) { unsigned r; asm volatile("v_cvt_pk_bf16_f32 %0, %1, %2" : "=v"(r) : "v"(lo), "v"(hi)); return r; }
;     __device__ __forceinline__ void operator()(Acc& acc, const Unit& u, int wr, int wc, int fr, int fq, LAS unsigned char*, const LAS float* rst) const {
;     ...
;                     for (int n = 0; n < 2; ++n) { const f32x4 v = acc[ai][bj][m][n] * rs; const int cc = cc0 + bj * 128 + n * 16;
;                         *(f32x4*)(dst + (size_t)row * 1024 + cc) = v;
;                         if (!isV) { u32x2 w; w.x = cvt_pk_bf16(v[0], v[1]); w.y = cvt_pk_bf16(v[2], v[3]); *(u32x2*)(Kb + ((size_t)l * 2048 + row) * 1024 + cc) = w; }
;                         else { u32x2 w; w.x = cvt_pk_bf16(v[0], v[1]); w.y = cvt_pk_bf16(v[2], v[3]); *(u32x2*)(Vt + ((size_t)l * 2048 + row) * 1024 + cc) = w; } }
.LBB0_294:
	s_add_u32 s10, s50, s10
	s_addc_u32 s11, s51, s11
	v_lshl_add_u64 v[36:37], s[10:11], 0, v[44:45]
	v_mov_b32_e32 v125, v133
	v_lshl_add_u64 v[36:37], v[36:37], 0, v[124:125]
	global_store_dwordx2 v[36:37], v[40:41], off offset:256
	v_mov_b32_e32 v36, v48
	v_mov_b32_e32 v37, v48
	v_pk_mul_f32 v[34:35], v[34:35], v[36:37]
	v_pk_mul_f32 v[32:33], v[32:33], v[48:49]
	s_and_b64 vcc, exec, s[0:1]
	s_mov_b64 s[10:11], -1
	global_store_dwordx4 v[50:51], v[32:35], off offset:576 sc1
	s_cbranch_vccnz .LBB0_296
	s_mov_b64 s[10:11], 0
	v_cvt_pk_bf16_f32 v36, v32, v33
	v_cvt_pk_bf16_f32 v37, v34, v35

; __device__ __forceinline__ unsigned cvt_pk_bf16(float lo, float hi) { unsigned r; asm volatile("v_cvt_pk_bf16_f32 %0, %1, %2" : "=v"(r) : "v"(lo), "v"(hi)); return r; }
;     __device__ __forceinline__ void operator()(Acc& acc, const Unit& u, int wr, int wc, int fr, int fq, LAS unsigned char*, const LAS float* rst) const {
;     ...
;                     for (int n = 0; n < 2; ++n) { const f32x4 v = acc[ai][bj][m][n] * rs; const int cc = cc0 + bj * 128 + n * 16;
;                         *(f32x4*)(dst + (size_t)row * 1024 + cc) = v;
;                         if (!isV) { u32x2 w; w.x = cvt_pk_bf16(v[0], v[1]); w.y = cvt_pk_bf16(v[2], v[3]); *(u32x2*)(Kb + ((size_t)l * 2048 + row) * 1024 + cc) = w; }
;                         else { u32x2 w; w.x = cvt_pk_bf16(v[0], v[1]); w.y = cvt_pk_bf16(v[2], v[3]); *(u32x2*)(Vt + ((size_t)l * 2048 + row) * 1024 + cc) = w; } }
.LBB0_298:
	s_add_u32 s10, s50, s10
	s_addc_u32 s11, s51, s11
	v_lshl_add_u64 v[32:33], s[10:11], 0, v[44:45]
	v_mov_b32_e32 v125, v133
	v_lshl_add_u64 v[32:33], v[32:33], 0, v[124:125]
	global_store_dwordx2 v[32:33], v[36:37], off offset:288
	v_mov_b32_e32 v32, v245
	v_add_u32_e32 v36, 0xa0, v138
	v_ashrrev_i32_e32 v37, 31, v36
	v_lshlrev_b64 v[34:35], 12, v[36:37]
	v_lshl_add_u64 v[34:35], s[20:21], 0, v[34:35]
	s_and_b64 vcc, exec, s[0:1]
	v_lshl_add_u64 v[34:35], v[34:35], 0, v[132:133]
	s_mov_b64 s[10:11], -1
	s_nop 0
	v_pk_mul_f32 v[30:31], v[30:31], v[32:33] op_sel_hi:[1,0]
	v_pk_mul_f32 v[28:29], v[28:29], v[32:33] op_sel_hi:[1,0]
	global_store_dwordx4 v[34:35], v[28:31], off sc1
	s_cbranch_vccnz .LBB0_300
	s_mov_b64 s[10:11], 0
	v_cvt_pk_bf16_f32 v38, v28, v29
	v_cvt_pk_bf16_f32 v39, v30, v31

; __device__ __forceinline__ unsigned cvt_pk_bf16(float lo, float hi) { unsigned r; asm volatile("v_cvt_pk_bf16_f32 %0, %1, %2" : "=v"(r) : "v"(lo), "v"(hi)); return r; }
;     __device__ __forceinline__ void operator()(Acc& acc, const Unit& u, int wr, int wc, int fr, int fq, LAS unsigned char*, const LAS float* rst) const {
;     ...
;                     for (int n = 0; n < 2; ++n) { const f32x4 v = acc[ai][bj][m][n] * rs; const int cc = cc0 + bj * 128 + n * 16;
;                         *(f32x4*)(dst + (size_t)row * 1024 + cc) = v;
;                         if (!isV) { u32x2 w; w.x = cvt_pk_bf16(v[0], v[1]); w.y = cvt_pk_bf16(v[2], v[3]); *(u32x2*)(Kb + ((size_t)l * 2048 + row) * 1024 + cc) = w; }
;                         else { u32x2 w; w.x = cvt_pk_bf16(v[0], v[1]); w.y = cvt_pk_bf16(v[2], v[3]); *(u32x2*)(Vt + ((size_t)l * 2048 + row) * 1024 + cc) = w; } }
.LBB0_302:
	v_lshl_add_u64 v[28:29], s[22:23], 0, v[36:37]
	s_add_u32 s10, s50, s10
	v_lshlrev_b64 v[28:29], 11, v[28:29]
	s_addc_u32 s11, s51, s11
	v_lshl_add_u64 v[30:31], s[10:11], 0, v[28:29]
	v_mov_b32_e32 v125, v133
	v_lshl_add_u64 v[30:31], v[30:31], 0, v[124:125]
	v_mov_b32_e32 v33, v32
	global_store_dwordx2 v[30:31], v[38:39], off
	v_mov_b32_e32 v30, v32
	v_mov_b32_e32 v31, v32
	v_pk_mul_f32 v[26:27], v[26:27], v[30:31]
	v_pk_mul_f32 v[24:25], v[24:25], v[32:33]
	s_and_b64 vcc, exec, s[0:1]
	s_mov_b64 s[10:11], -1
	global_store_dwordx4 v[34:35], v[24:27], off offset:64 sc1
	s_cbranch_vccnz .LBB0_304
	s_mov_b64 s[10:11], 0
	v_cvt_pk_bf16_f32 v30, v24, v25
	v_cvt_pk_bf16_f32 v31, v26, v27

; __device__ __forceinline__ unsigned cvt_pk_bf16(float lo, float hi) { unsigned r; asm volatile("v_cvt_pk_bf16_f32 %0, %1, %2" : "=v"(r) : "v"(lo), "v"(hi)); return r; }
;     __device__ __forceinline__ void operator()(Acc& acc, const Unit& u, int wr, int wc, int fr, int fq, LAS unsigned char*, const LAS float* rst) const {
;     ...
;                     for (int n = 0; n < 2; ++n) { const f32x4 v = acc[ai][bj][m][n] * rs; const int cc = cc0 + bj * 128 + n * 16;
;                         *(f32x4*)(dst + (size_t)row * 1024 + cc) = v;
;                         if (!isV) { u32x2 w; w.x = cvt_pk_bf16(v[0], v[1]); w.y = cvt_pk_bf16(v[2], v[3]); *(u32x2*)(Kb + ((size_t)l * 2048 + row) * 1024 + cc) = w; }
;                         else { u32x2 w; w.x = cvt_pk_bf16(v[0], v[1]); w.y = cvt_pk_bf16(v[2], v[3]); *(u32x2*)(Vt + ((size_t)l * 2048 + row) * 1024 + cc) = w; } }
.LBB0_306:
	s_add_u32 s10, s50, s10
	s_addc_u32 s11, s51, s11
	v_lshl_add_u64 v[24:25], s[10:11], 0, v[28:29]
	v_mov_b32_e32 v125, v133
	v_lshl_add_u64 v[24:25], v[24:25], 0, v[124:125]
	global_store_dwordx2 v[24:25], v[30:31], off offset:32
	v_mov_b32_e32 v24, v32
	v_mov_b32_e32 v25, v32
	v_pk_mul_f32 v[22:23], v[22:23], v[24:25]
	v_pk_mul_f32 v[20:21], v[20:21], v[32:33]
	s_and_b64 vcc, exec, s[0:1]
	s_mov_b64 s[10:11], -1
	global_store_dwordx4 v[34:35], v[20:23], off offset:512 sc1
	s_cbranch_vccnz .LBB0_308
	s_mov_b64 s[10:11], 0
	v_cvt_pk_bf16_f32 v24, v20, v21
	v_cvt_pk_bf16_f32 v25, v22, v23

; __device__ __forceinline__ unsigned cvt_pk_bf16(float lo, float hi) { unsigned r; asm volatile("v_cvt_pk_bf16_f32 %0, %1, %2" : "=v"(r) : "v"(lo), "v"(hi)); return r; }
;     __device__ __forceinline__ void operator()(Acc& acc, const Unit& u, int wr, int wc, int fr, int fq, LAS unsigned char*, const LAS float* rst) const {
;     ...
;                     for (int n = 0; n < 2; ++n) { const f32x4 v = acc[ai][bj][m][n] * rs; const int cc = cc0 + bj * 128 + n * 16;
;                         *(f32x4*)(dst + (size_t)row * 1024 + cc) = v;
;                         if (!isV) { u32x2 w; w.x = cvt_pk_bf16(v[0], v[1]); w.y = cvt_pk_bf16(v[2], v[3]); *(u32x2*)(Kb + ((size_t)l * 2048 + row) * 1024 + cc) = w; }
;                         else { u32x2 w; w.x = cvt_pk_bf16(v[0], v[1]); w.y = cvt_pk_bf16(v[2], v[3]); *(u32x2*)(Vt + ((size_t)l * 2048 + row) * 1024 + cc) = w; } }
.LBB0_310:
	s_add_u32 s10, s50, s10
	s_addc_u32 s11, s51, s11
	v_lshl_add_u64 v[20:21], s[10:11], 0, v[28:29]
	v_mov_b32_e32 v125, v133
	v_lshl_add_u64 v[20:21], v[20:21], 0, v[124:125]
	global_store_dwordx2 v[20:21], v[24:25], off offset:256
	v_mov_b32_e32 v20, v32
	v_mov_b32_e32 v21, v32
	v_pk_mul_f32 v[18:19], v[18:19], v[20:21]
	v_pk_mul_f32 v[16:17], v[16:17], v[32:33]
	s_and_b64 vcc, exec, s[0:1]
	s_mov_b64 s[10:11], -1
	global_store_dwordx4 v[34:35], v[16:19], off offset:576 sc1
	s_cbranch_vccnz .LBB0_312
	s_mov_b64 s[10:11], 0
	v_cvt_pk_bf16_f32 v20, v16, v17
	v_cvt_pk_bf16_f32 v21, v18, v19

; __device__ __forceinline__ unsigned cvt_pk_bf16(float lo, float hi) { unsigned r; asm volatile("v_cvt_pk_bf16_f32 %0, %1, %2" : "=v"(r) : "v"(lo), "v"(hi)); return r; }
;     __device__ __forceinline__ void operator()(Acc& acc, const Unit& u, int wr, int wc, int fr, int fq, LAS unsigned char*, const LAS float* rst) const {
;     ...
;                     for (int n = 0; n < 2; ++n) { const f32x4 v = acc[ai][bj][m][n] * rs; const int cc = cc0 + bj * 128 + n * 16;
;                         *(f32x4*)(dst + (size_t)row * 1024 + cc) = v;
;                         if (!isV) { u32x2 w; w.x = cvt_pk_bf16(v[0], v[1]); w.y = cvt_pk_bf16(v[2], v[3]); *(u32x2*)(Kb + ((size_t)l * 2048 + row) * 1024 + cc) = w; }
;                         else { u32x2 w; w.x = cvt_pk_bf16(v[0], v[1]); w.y = cvt_pk_bf16(v[2], v[3]); *(u32x2*)(Vt + ((size_t)l * 2048 + row) * 1024 + cc) = w; } }
.LBB0_314:
	s_add_u32 s10, s50, s10
	s_addc_u32 s11, s51, s11
	v_lshl_add_u64 v[16:17], s[10:11], 0, v[28:29]
	v_mov_b32_e32 v125, v133
	v_lshl_add_u64 v[16:17], v[16:17], 0, v[124:125]
	global_store_dwordx2 v[16:17], v[20:21], off offset:288
	v_mov_b32_e32 v16, v246
	v_add_u32_e32 v20, 0xb0, v138
	v_ashrrev_i32_e32 v21, 31, v20
	v_lshlrev_b64 v[18:19], 12, v[20:21]
	v_lshl_add_u64 v[18:19], s[20:21], 0, v[18:19]
	s_and_b64 vcc, exec, s[0:1]
	v_lshl_add_u64 v[18:19], v[18:19], 0, v[132:133]
	s_mov_b64 s[10:11], -1
	s_nop 0
	v_pk_mul_f32 v[14:15], v[14:15], v[16:17] op_sel_hi:[1,0]
	v_pk_mul_f32 v[12:13], v[12:13], v[16:17] op_sel_hi:[1,0]
	global_store_dwordx4 v[18:19], v[12:15], off sc1
	s_cbranch_vccnz .LBB0_316
	s_mov_b64 s[10:11], 0
	v_cvt_pk_bf16_f32 v22, v12, v13
	v_cvt_pk_bf16_f32 v23, v14, v15

; __device__ __forceinline__ unsigned cvt_pk_bf16(float lo, float hi) { unsigned r; asm volatile("v_cvt_pk_bf16_f32 %0, %1, %2" : "=v"(r) : "v"(lo), "v"(hi)); return r; }
;     __device__ __forceinline__ void operator()(Acc& acc, const Unit& u, int wr, int wc, int fr, int fq, LAS unsigned char*, const LAS float* rst) const {
;     ...
;                     for (int n = 0; n < 2; ++n) { const f32x4 v = acc[ai][bj][m][n] * rs; const int cc = cc0 + bj * 128 + n * 16;
;                         *(f32x4*)(dst + (size_t)row * 1024 + cc) = v;
;                         if (!isV) { u32x2 w; w.x = cvt_pk_bf16(v[0], v[1]); w.y = cvt_pk_bf16(v[2], v[3]); *(u32x2*)(Kb + ((size_t)l * 2048 + row) * 1024 + cc) = w; }
;                         else { u32x2 w; w.x = cvt_pk_bf16(v[0], v[1]); w.y = cvt_pk_bf16(v[2], v[3]); *(u32x2*)(Vt + ((size_t)l * 2048 + row) * 1024 + cc) = w; } }
.LBB0_318:
	v_lshl_add_u64 v[12:13], s[22:23], 0, v[20:21]
	s_add_u32 s10, s50, s10
	v_lshlrev_b64 v[12:13], 11, v[12:13]
	s_addc_u32 s11, s51, s11
	v_lshl_add_u64 v[14:15], s[10:11], 0, v[12:13]
	v_mov_b32_e32 v125, v133
	v_lshl_add_u64 v[14:15], v[14:15], 0, v[124:125]
	v_mov_b32_e32 v17, v16
	global_store_dwordx2 v[14:15], v[22:23], off
	v_mov_b32_e32 v14, v16
	v_mov_b32_e32 v15, v16
	v_pk_mul_f32 v[10:11], v[10:11], v[14:15]
	v_pk_mul_f32 v[8:9], v[8:9], v[16:17]
	s_and_b64 vcc, exec, s[0:1]
	s_mov_b64 s[10:11], -1
	global_store_dwordx4 v[18:19], v[8:11], off offset:64 sc1
	s_cbranch_vccnz .LBB0_320
	s_mov_b64 s[10:11], 0
	v_cvt_pk_bf16_f32 v14, v8, v9
	v_cvt_pk_bf16_f32 v15, v10, v11

; __device__ __forceinline__ unsigned cvt_pk_bf16(float lo, float hi) { unsigned r; asm volatile("v_cvt_pk_bf16_f32 %0, %1, %2" : "=v"(r) : "v"(lo), "v"(hi)); return r; }
;     __device__ __forceinline__ void operator()(Acc& acc, const Unit& u, int wr, int wc, int fr, int fq, LAS unsigned char*, const LAS float* rst) const {
;     ...
;                     for (int n = 0; n < 2; ++n) { const f32x4 v = acc[ai][bj][m][n] * rs; const int cc = cc0 + bj * 128 + n * 16;
;                         *(f32x4*)(dst + (size_t)row * 1024 + cc) = v;
;                         if (!isV) { u32x2 w; w.x = cvt_pk_bf16(v[0], v[1]); w.y = cvt_pk_bf16(v[2], v[3]); *(u32x2*)(Kb + ((size_t)l * 2048 + row) * 1024 + cc) = w; }
;                         else { u32x2 w; w.x = cvt_pk_bf16(v[0], v[1]); w.y = cvt_pk_bf16(v[2], v[3]); *(u32x2*)(Vt + ((size_t)l * 2048 + row) * 1024 + cc) = w; } }
.LBB0_322:
	s_add_u32 s10, s50, s10
	s_addc_u32 s11, s51, s11
	v_lshl_add_u64 v[8:9], s[10:11], 0, v[12:13]
	v_mov_b32_e32 v125, v133
	v_lshl_add_u64 v[8:9], v[8:9], 0, v[124:125]
	global_store_dwordx2 v[8:9], v[14:15], off offset:32
	v_mov_b32_e32 v8, v16
	v_mov_b32_e32 v9, v16
	v_pk_mul_f32 v[6:7], v[6:7], v[8:9]
	v_pk_mul_f32 v[4:5], v[4:5], v[16:17]
	s_and_b64 vcc, exec, s[0:1]
	s_mov_b64 s[10:11], -1
	global_store_dwordx4 v[18:19], v[4:7], off offset:512 sc1
	s_cbranch_vccnz .LBB0_324
	s_mov_b64 s[10:11], 0
	v_cvt_pk_bf16_f32 v8, v4, v5
	v_cvt_pk_bf16_f32 v9, v6, v7

; __device__ __forceinline__ unsigned cvt_pk_bf16(float lo, float hi) { unsigned r; asm volatile("v_cvt_pk_bf16_f32 %0, %1, %2" : "=v"(r) : "v"(lo), "v"(hi)); return r; }
;     __device__ __forceinline__ void operator()(Acc& acc, const Unit& u, int wr, int wc, int fr, int fq, LAS unsigned char*, const LAS float* rst) const {
;     ...
;                     for (int n = 0; n < 2; ++n) { const f32x4 v = acc[ai][bj][m][n] * rs; const int cc = cc0 + bj * 128 + n * 16;
;                         *(f32x4*)(dst + (size_t)row * 1024 + cc) = v;
;                         if (!isV) { u32x2 w; w.x = cvt_pk_bf16(v[0], v[1]); w.y = cvt_pk_bf16(v[2], v[3]); *(u32x2*)(Kb + ((size_t)l * 2048 + row) * 1024 + cc) = w; }
;                         else { u32x2 w; w.x = cvt_pk_bf16(v[0], v[1]); w.y = cvt_pk_bf16(v[2], v[3]); *(u32x2*)(Vt + ((size_t)l * 2048 + row) * 1024 + cc) = w; } }
.LBB0_326:
	s_add_u32 s10, s50, s10
	s_addc_u32 s11, s51, s11
	v_lshl_add_u64 v[4:5], s[10:11], 0, v[12:13]
	v_mov_b32_e32 v125, v133
	v_lshl_add_u64 v[4:5], v[4:5], 0, v[124:125]
	global_store_dwordx2 v[4:5], v[8:9], off offset:256
	v_mov_b32_e32 v4, v16
	v_mov_b32_e32 v5, v16
	v_pk_mul_f32 v[2:3], v[2:3], v[4:5]
	v_pk_mul_f32 v[0:1], v[0:1], v[16:17]
	s_and_b64 vcc, exec, s[0:1]
	s_mov_b64 s[0:1], -1
	global_store_dwordx4 v[18:19], v[0:3], off offset:576 sc1
	s_cbranch_vccnz .LBB0_328
	s_mov_b64 s[0:1], 0
	v_cvt_pk_bf16_f32 v4, v0, v1
	v_cvt_pk_bf16_f32 v5, v2, v3

; __device__ __forceinline__ float bf_lo(unsigned w) { return __uint_as_float(w << 16); }
; __device__ __forceinline__ float bf_hi(unsigned w) { return __uint_as_float(w & 0xffff0000u); }
; __device__ __forceinline__ void final_norm(Frame& F) {
;     ...
;     for (int m = gw; m < MT; m += NGW) {
;         const float rs = row_rstd(ssq, m);
;         f32x4* yr = (f32x4*)(F.out + (size_t)m * D) + lane; const u32x2* xr = (const u32x2*)((const bf16_t*)(F.ws + WS_XB) + (size_t)m * D) + lane;
; #pragma unroll
;         for (int j = 0; j < 4; ++j) { const u32x2 o = xr[64 * j]; yr[64 * j] = (f32x4){bf_lo(o.x), bf_hi(o.x), bf_lo(o.y), bf_hi(o.y)} * rs * gv[j]; }
;     }
.LBB0_826:
	v_lshl_add_u64 v[22:23], s[38:39], 0, v[16:17]
	s_add_u32 s11, s38, s2
	v_add_co_u32_e32 v38, vcc, s10, v22
	s_addc_u32 s12, s39, s3
	v_mov_b32_e32 v21, s11
	v_addc_co_u32_e32 v39, vcc, 0, v23, vcc
	v_add_co_u32_e32 v40, vcc, 0x100000, v21
	v_mov_b32_e32 v21, s12
	s_nop 0
	v_addc_co_u32_e32 v41, vcc, 0, v21, vcc
	flat_load_dwordx4 v[22:25], v[40:41]
	flat_load_dwordx4 v[26:29], v[40:41] offset:16
	flat_load_dwordx4 v[30:33], v[40:41] offset:32
	flat_load_dwordx4 v[34:37], v[40:41] offset:48
	flat_load_dwordx2 v[42:43], v[38:39]
	s_add_i32 s8, s8, s14
	s_add_u32 s2, s2, s4
	s_addc_u32 s3, s3, s5
	v_lshl_add_u64 v[16:17], v[16:17], 0, s[0:1]
	s_cmp_lt_i32 s8, 0x8100
	s_waitcnt vmcnt(0) lgkmcnt(0)
	v_mov_b32_e32 v44, v22
	v_mov_b32_e32 v22, v24
	v_mov_b32_e32 v45, v30
	v_mov_b32_e32 v30, v23
	v_mov_b32_e32 v23, v32
	v_mov_b32_e32 v32, v25
	v_mov_b32_e32 v24, v26
	v_mov_b32_e32 v25, v34
	v_mov_b32_e32 v34, v27
	v_mov_b32_e32 v26, v28
	v_mov_b32_e32 v27, v36
	v_mov_b32_e32 v36, v29
	v_pk_add_f32 v[28:29], v[44:45], v[30:31]
	v_pk_add_f32 v[22:23], v[22:23], v[32:33]
	v_pk_add_f32 v[24:25], v[24:25], v[34:35]
	v_pk_add_f32 v[26:27], v[26:27], v[36:37]
	v_pk_add_f32 v[22:23], v[28:29], v[22:23]
	v_pk_add_f32 v[24:25], v[24:25], v[26:27]
	v_lshlrev_b32_e32 v40, 16, v42
	v_pk_add_f32 v[22:23], v[22:23], v[24:25]
	v_and_b32_e32 v41, 0xffff0000, v42
	v_add_f32_e32 v21, v22, v23
	v_fmamk_f32 v21, v21, 0x3a800000, v20
	v_mul_f32_e32 v22, 0x4b800000, v21
	v_cmp_gt_f32_e32 vcc, s9, v21
	v_lshlrev_b32_e32 v42, 16, v43
	v_and_b32_e32 v43, 0xffff0000, v43
	v_cndmask_b32_e32 v21, v21, v22, vcc
	v_rsq_f32_e32 v21, v21
	s_nop 0
	v_mul_f32_e32 v22, 0x45800000, v21
	v_cndmask_b32_e32 v26, v21, v22, vcc
	v_pk_mul_f32 v[22:23], v[26:27], v[40:41] op_sel_hi:[0,1]
	v_pk_mul_f32 v[24:25], v[26:27], v[42:43] op_sel_hi:[0,1]
	v_pk_mul_f32 v[24:25], v[2:3], v[24:25]
	v_pk_mul_f32 v[22:23], v[0:1], v[22:23]
	flat_store_dwordx4 v[18:19], v[22:25] sc1
	flat_load_dwordx2 v[22:23], v[38:39] offset:512
	s_waitcnt vmcnt(0) lgkmcnt(0)
	v_lshlrev_b32_e32 v24, 16, v22
	v_and_b32_e32 v25, 0xffff0000, v22
	v_lshlrev_b32_e32 v22, 16, v23
	v_and_b32_e32 v23, 0xffff0000, v23
	v_pk_mul_f32 v[28:29], v[26:27], v[24:25] op_sel_hi:[0,1]
	v_pk_mul_f32 v[22:23], v[26:27], v[22:23] op_sel_hi:[0,1]
	v_pk_mul_f32 v[24:25], v[6:7], v[22:23]
	v_pk_mul_f32 v[22:23], v[4:5], v[28:29]
	flat_store_dwordx4 v[18:19], v[22:25] offset:1024 sc1
	flat_load_dwordx2 v[22:23], v[38:39] offset:1024
	s_waitcnt vmcnt(0) lgkmcnt(0)
	v_lshlrev_b32_e32 v24, 16, v22
	v_and_b32_e32 v25, 0xffff0000, v22
	v_lshlrev_b32_e32 v22, 16, v23
	v_and_b32_e32 v23, 0xffff0000, v23
	v_pk_mul_f32 v[28:29], v[26:27], v[24:25] op_sel_hi:[0,1]
	v_pk_mul_f32 v[22:23], v[26:27], v[22:23] op_sel_hi:[0,1]
	v_pk_mul_f32 v[24:25], v[10:11], v[22:23]
	v_pk_mul_f32 v[22:23], v[8:9], v[28:29]
	flat_store_dwordx4 v[18:19], v[22:25] offset:2048 sc1
	flat_load_dwordx2 v[22:23], v[38:39] offset:1536
	s_waitcnt vmcnt(0) lgkmcnt(0)
	v_lshlrev_b32_e32 v24, 16, v22
	v_and_b32_e32 v25, 0xffff0000, v22
	v_lshlrev_b32_e32 v22, 16, v23
	v_and_b32_e32 v23, 0xffff0000, v23
	v_pk_mul_f32 v[28:29], v[26:27], v[24:25] op_sel_hi:[0,1]
	v_pk_mul_f32 v[22:23], v[26:27], v[22:23] op_sel_hi:[0,1]
	v_pk_mul_f32 v[24:25], v[14:15], v[22:23]
	v_pk_mul_f32 v[22:23], v[12:13], v[28:29]
	flat_store_dwordx4 v[18:19], v[22:25] offset:3072 sc1
	v_lshl_add_u64 v[18:19], v[18:19], 0, s[6:7]
	s_cbranch_scc1 .LBB0_826
